# FFN-up -> down per-panel counters when each blockIdx&7 class is verified to sit on one XCD (consistency check via umax words)
# speedup vs baseline: 1.0034x; 1.0034x over previous
_Z11mega_kernel6Paramsii:
	s_mov_b32 s101, 0
	s_load_dword s21, s[0:1], 0x138
	v_writelane_b32 v253, s2, 0
	s_add_u32 s2, s0, 0x138
	s_addc_u32 s3, s1, 0
	v_writelane_b32 v253, s2, 1
	v_and_b32_e32 v1, 0x3ff, v0
	s_nop 0
	v_writelane_b32 v253, s3, 2
	s_mov_b32 s2, 0
	s_ashr_i32 s3, s2, 31
	s_add_u32 s2, s0, s2
	v_writelane_b32 v253, s0, 3
	s_addc_u32 s3, s1, s3
	s_nop 0
	v_writelane_b32 v253, s1, 4
	s_load_dwordx2 s[0:1], s[2:3], 0xb8
	v_cmp_eq_u32_e64 s[2:3], 0, v1
	s_waitcnt lgkmcnt(0)
	v_writelane_b32 v253, s0, 5
	s_nop 1
	v_writelane_b32 v253, s1, 6
	s_getreg_b32 s0, hwreg(HW_REG_XCC_ID, 0, 4)
	s_and_b32 s4, s0, 15
	s_mov_b64 s[0:1], exec
	v_writelane_b32 v253, s2, 7
	s_nop 1
	v_writelane_b32 v253, s3, 8
	s_and_b64 s[2:3], s[0:1], s[2:3]
	s_mov_b64 exec, s[2:3]
	s_cbranch_execz .LBB0_3
	s_add_i32 s5, 0, 0x24000
	s_cmp_lg_u32 s5, -1
	s_mov_b64 s[6:7], src_shared_base
	s_cselect_b32 s5, s5, 0
	s_cselect_b32 s6, s7, 0
	v_mov_b32_e32 v2, s5
	s_add_i32 s5, 0, 0x24004
	s_cmp_lg_u32 s5, -1
	v_mov_b32_e32 v3, s6
	v_mov_b32_e32 v4, 0
	s_cselect_b32 s5, s5, 0
	s_cselect_b32 s6, s7, 0
	s_mov_b64 s[2:3], exec
	flat_store_dword v[2:3], v4 sc0 sc1
	s_waitcnt vmcnt(0)
	v_mov_b32_e32 v2, s5
	v_mov_b32_e32 v3, s6
	flat_store_dword v[2:3], v4 sc0 sc1
	s_waitcnt vmcnt(0)
	v_mbcnt_lo_u32_b32 v2, s2, 0
	v_mbcnt_hi_u32_b32 v2, s3, v2
	v_cmp_eq_u32_e32 vcc, 0, v2
	s_and_b64 s[6:7], exec, vcc
	s_mov_b64 exec, s[6:7]
	s_cbranch_execz .LBB0_3
	s_bcnt1_i32_b64 s2, s[2:3]
	s_lshl_b32 s5, s4, 8
	v_mov_b32_e32 v3, s2
	v_readlane_b32 s2, v253, 5
	v_mov_b32_e32 v2, s5
	v_readlane_b32 s3, v253, 6
	s_nop 4
	global_atomic_add v2, v3, s[2:3] offset:1024
	v_readlane_b32 s5, v253, 0
	s_and_b32 s5, s5, 7
	s_lshl_b32 s5, s5, 2
	v_mov_b32_e32 v2, s5
	s_add_i32 s5, s4, 1
	v_mov_b32_e32 v3, s5
	global_atomic_umax v2, v3, s[2:3] offset:384
	s_sub_i32 s5, 16, s4
	v_mov_b32_e32 v3, s5
	global_atomic_umax v2, v3, s[2:3] offset:416

.LBB0_8:
	v_writelane_b32 v254, s78, 24
	s_mov_b32 s0, s49
	s_ashr_i32 s1, s0, 31
	v_writelane_b32 v254, s79, 25
	v_writelane_b32 v254, s76, 26
	v_readlane_b32 s2, v253, 3
	v_readlane_b32 s3, v253, 4
	v_writelane_b32 v254, s77, 27
	v_writelane_b32 v254, s74, 28
	s_add_u32 s0, s2, s0
	s_addc_u32 s1, s3, s1
	v_writelane_b32 v254, s75, 29
	v_writelane_b32 v254, s66, 30
	v_readlane_b32 s24, v253, 62
	v_writelane_b32 v254, s67, 31
	v_readlane_b32 s25, v253, 63
	s_load_dwordx16 s[52:67], s[0:1], 0x0
	s_load_dwordx2 s[30:31], s[0:1], 0x70
	s_load_dwordx4 s[36:39], s[0:1], 0x60
	s_load_dwordx8 s[12:19], s[0:1], 0x40
	s_load_dwordx2 s[2:3], s[0:1], 0x88
	s_load_dwordx8 s[68:75], s[0:1], 0x98
	s_load_dwordx16 s[80:95], s[0:1], 0xc0
	s_load_dwordx4 s[96:99], s[0:1], 0x120
	s_load_dwordx8 s[4:11], s[0:1], 0x100
	s_waitcnt lgkmcnt(0)
	s_cmp_eq_u32 s46, 1
	s_cbranch_scc0 .Lpf_nodec
	v_readlane_b32 s0, v253, 5
	v_readlane_b32 s1, v253, 6
	v_lshlrev_b32_e32 v2, 2, v194
	s_nop 3
	s_mov_b64 exec, 0xff
	global_load_dword v3, v2, s[0:1] offset:384 sc1
	global_load_dword v4, v2, s[0:1] offset:416 sc1
	s_waitcnt vmcnt(0)
	v_add_u32_e32 v3, v3, v4
	v_cmp_ne_u32_e32 vcc, 17, v3
	s_mov_b64 exec, -1
	s_cmp_eq_u64 vcc, 0
	s_cselect_b32 s0, 1, 0
	v_writelane_b32 v252, s0, 40
